# FFN-in K-loop back-edge rotation: loop-control SALU moved into the MFMA shadow of the last compute block; loop head is the first ds_read
# speedup vs baseline: 1.0043x; 1.0043x over previous
.LBB0_1001:
	s_ashr_i32 s17, s16, 31
	s_lshl_b64 s[18:19], s[16:17], 19
	s_add_u32 s18, s92, s18
	s_addc_u32 s19, s93, s19
	s_and_b64 s[20:21], s[6:7], exec
	s_cselect_b32 s17, s19, s29
	s_cselect_b32 s51, s18, s28
	s_ashr_i32 s15, s14, 31
	s_lshl_b64 s[20:21], s[14:15], 19
	s_add_u32 s20, s41, s20
	s_addc_u32 s21, s42, s21
	s_and_b64 s[30:31], s[6:7], exec
	s_cselect_b32 s15, s21, s25
	s_cselect_b32 s52, s20, s24
	s_add_u32 s53, s24, 0x100
	s_addc_u32 s61, s25, 0
	s_add_u32 s24, s28, 0x40080
	s_addc_u32 s25, s29, 0
	s_mov_b32 s62, -2
	s_add_u32 s28, s24, 0xfffc0080
	s_addc_u32 s29, s25, -1
	s_add_i32 s63, 0, 0x10000
	s_cmp_eq_u32 s62, 12
	s_cselect_b32 s31, s17, s29
	s_cselect_b32 s30, s51, s28
	v_add_u32_e32 v140, s63, v143
	s_cselect_b32 s29, s15, s61
	s_cselect_b32 s28, s52, s53
	s_add_i32 s72, 0, 0x14000
	ds_read_b128 v[146:149], v140
	ds_read_b128 v[150:153], v140 offset:1024
	ds_read_b128 v[154:157], v140 offset:2048
	ds_read_b128 v[158:161], v140 offset:3072
	v_add_u32_e32 v140, s72, v143
	ds_read_b128 v[162:165], v140
	ds_read_b128 v[166:169], v140 offset:1024
	ds_read_b128 v[170:173], v140 offset:2048
	ds_read_b128 v[174:177], v140 offset:3072
	v_lshl_add_u64 v[140:141], s[24:25], 0, v[138:139]
	s_add_i32 m0, s23, 0xc000
	ds_read_b128 v[178:181], v145
	ds_read_b128 v[182:185], v145 offset:1024
	ds_read_b128 v[186:189], v145 offset:2048
	ds_read_b128 v[190:193], v145 offset:3072
	ds_read_b128 v[194:197], v145 offset:4096
	ds_read_b128 v[198:201], v145 offset:5120
	ds_read_b128 v[202:205], v145 offset:6144
	ds_read_b128 v[206:209], v145 offset:7168
	global_load_lds_dwordx4 v[140:141], off
	v_lshl_add_u64 v[140:141], s[24:25], 0, v[136:137]
	s_add_i32 m0, s23, 0xe000
	s_nop 0
	global_load_lds_dwordx4 v[140:141], off
	s_waitcnt vmcnt(8)
	s_waitcnt lgkmcnt(0)
	s_barrier
	s_setprio 1
	s_waitcnt lgkmcnt(0)
	v_mfma_f32_16x16x32_bf16 v[126:129], v[146:149], v[178:181], 0
	v_mfma_f32_16x16x32_bf16 v[122:125], v[154:157], v[178:181], 0
	v_mfma_f32_16x16x32_bf16 v[110:113], v[146:149], v[186:189], 0
	v_mfma_f32_16x16x32_bf16 v[106:109], v[154:157], v[186:189], 0
	v_mfma_f32_16x16x32_bf16 v[94:97], v[146:149], v[194:197], 0
	v_mfma_f32_16x16x32_bf16 v[90:93], v[154:157], v[194:197], 0
	v_mfma_f32_16x16x32_bf16 v[78:81], v[146:149], v[202:205], 0
	v_mfma_f32_16x16x32_bf16 v[74:77], v[154:157], v[202:205], 0
	v_mfma_f32_16x16x32_bf16 v[126:129], v[150:153], v[182:185], v[126:129]
	v_mfma_f32_16x16x32_bf16 v[122:125], v[158:161], v[182:185], v[122:125]
	v_mfma_f32_16x16x32_bf16 v[110:113], v[150:153], v[190:193], v[110:113]
	v_mfma_f32_16x16x32_bf16 v[106:109], v[158:161], v[190:193], v[106:109]
	v_mfma_f32_16x16x32_bf16 v[94:97], v[150:153], v[198:201], v[94:97]
	v_mfma_f32_16x16x32_bf16 v[90:93], v[158:161], v[198:201], v[90:93]
	v_mfma_f32_16x16x32_bf16 v[78:81], v[150:153], v[206:209], v[78:81]
	v_mfma_f32_16x16x32_bf16 v[74:77], v[158:161], v[206:209], v[74:77]
	s_setprio 0
	s_setprio 1
	v_mfma_f32_16x16x32_bf16 v[118:121], v[162:165], v[178:181], 0
	v_mfma_f32_16x16x32_bf16 v[114:117], v[170:173], v[178:181], 0
	v_mfma_f32_16x16x32_bf16 v[102:105], v[162:165], v[186:189], 0
	v_mfma_f32_16x16x32_bf16 v[98:101], v[170:173], v[186:189], 0
	v_mfma_f32_16x16x32_bf16 v[86:89], v[162:165], v[194:197], 0
	v_mfma_f32_16x16x32_bf16 v[82:85], v[170:173], v[194:197], 0
	v_mfma_f32_16x16x32_bf16 v[70:73], v[162:165], v[202:205], 0
	v_mfma_f32_16x16x32_bf16 v[66:69], v[170:173], v[202:205], 0
	v_mfma_f32_16x16x32_bf16 v[118:121], v[166:169], v[182:185], v[118:121]
	v_mfma_f32_16x16x32_bf16 v[114:117], v[174:177], v[182:185], v[114:117]
	v_mfma_f32_16x16x32_bf16 v[102:105], v[166:169], v[190:193], v[102:105]
	v_mfma_f32_16x16x32_bf16 v[98:101], v[174:177], v[190:193], v[98:101]
	v_mfma_f32_16x16x32_bf16 v[86:89], v[166:169], v[198:201], v[86:89]
	v_mfma_f32_16x16x32_bf16 v[82:85], v[174:177], v[198:201], v[82:85]
	v_mfma_f32_16x16x32_bf16 v[70:73], v[166:169], v[206:209], v[70:73]
	v_mfma_f32_16x16x32_bf16 v[66:69], v[174:177], v[206:209], v[66:69]
	s_setprio 0
	s_barrier
	s_add_i32 s63, s63, s40
	v_lshl_add_u64 v[140:141], s[28:29], 0, v[0:1]
	s_mov_b32 m0, s63
	ds_read_b128 v[178:181], v145 offset:16384
	ds_read_b128 v[182:185], v145 offset:17408
	ds_read_b128 v[186:189], v145 offset:18432
	ds_read_b128 v[190:193], v145 offset:19456
	ds_read_b128 v[194:197], v145 offset:20480
	ds_read_b128 v[198:201], v145 offset:21504
	ds_read_b128 v[202:205], v145 offset:22528
	ds_read_b128 v[206:209], v145 offset:23552
	global_load_lds_dwordx4 v[140:141], off
	s_add_i32 m0, s63, 0x2000
	s_add_u32 s70, s28, 0x40000
	v_lshl_add_u64 v[210:211], s[28:29], 0, v[134:135]
	s_addc_u32 s71, s29, 0
	s_add_i32 s63, s72, s40
	global_load_lds_dwordx4 v[210:211], off
	v_lshl_add_u64 v[212:213], s[70:71], 0, v[0:1]
	s_mov_b32 m0, s63
	v_lshl_add_u64 v[214:215], s[30:31], 0, v[132:133]
	global_load_lds_dwordx4 v[212:213], off
	v_lshl_add_u64 v[212:213], s[70:71], 0, v[134:135]
	s_add_i32 m0, s63, 0x2000
	s_nop 0
	global_load_lds_dwordx4 v[212:213], off
	v_lshl_add_u64 v[212:213], s[30:31], 0, v[130:131]
	s_mov_b32 m0, s23
	s_nop 0
	global_load_lds_dwordx4 v[212:213], off
	s_mov_b32 m0, s43
	s_nop 0
	global_load_lds_dwordx4 v[214:215], off
	s_waitcnt vmcnt(8)
	s_waitcnt lgkmcnt(0)
	s_barrier
	s_setprio 1
	s_waitcnt lgkmcnt(0)
	v_mfma_f32_16x16x32_bf16 v[62:65], v[146:149], v[178:181], 0
	v_mfma_f32_16x16x32_bf16 v[58:61], v[154:157], v[178:181], 0
	v_mfma_f32_16x16x32_bf16 v[46:49], v[146:149], v[186:189], 0
	v_mfma_f32_16x16x32_bf16 v[42:45], v[154:157], v[186:189], 0
	v_mfma_f32_16x16x32_bf16 v[30:33], v[146:149], v[194:197], 0
	v_mfma_f32_16x16x32_bf16 v[26:29], v[154:157], v[194:197], 0
	v_mfma_f32_16x16x32_bf16 v[14:17], v[146:149], v[202:205], 0
	v_mfma_f32_16x16x32_bf16 v[10:13], v[154:157], v[202:205], 0
	v_mfma_f32_16x16x32_bf16 v[62:65], v[150:153], v[182:185], v[62:65]
	v_mfma_f32_16x16x32_bf16 v[58:61], v[158:161], v[182:185], v[58:61]
	v_mfma_f32_16x16x32_bf16 v[46:49], v[150:153], v[190:193], v[46:49]
	v_mfma_f32_16x16x32_bf16 v[42:45], v[158:161], v[190:193], v[42:45]
	v_mfma_f32_16x16x32_bf16 v[30:33], v[150:153], v[198:201], v[30:33]
	v_mfma_f32_16x16x32_bf16 v[26:29], v[158:161], v[198:201], v[26:29]
	v_mfma_f32_16x16x32_bf16 v[14:17], v[150:153], v[206:209], v[14:17]
	v_mfma_f32_16x16x32_bf16 v[10:13], v[158:161], v[206:209], v[10:13]
	s_setprio 0
	s_setprio 1
	v_mfma_f32_16x16x32_bf16 v[54:57], v[162:165], v[178:181], 0
	v_mfma_f32_16x16x32_bf16 v[50:53], v[170:173], v[178:181], 0
	v_mfma_f32_16x16x32_bf16 v[38:41], v[162:165], v[186:189], 0
	v_mfma_f32_16x16x32_bf16 v[34:37], v[170:173], v[186:189], 0
	v_mfma_f32_16x16x32_bf16 v[22:25], v[162:165], v[194:197], 0
	v_mfma_f32_16x16x32_bf16 v[18:21], v[170:173], v[194:197], 0
	v_mfma_f32_16x16x32_bf16 v[6:9], v[162:165], v[202:205], 0
	v_mfma_f32_16x16x32_bf16 v[2:5], v[170:173], v[202:205], 0
	v_mfma_f32_16x16x32_bf16 v[54:57], v[166:169], v[182:185], v[54:57]
	v_mfma_f32_16x16x32_bf16 v[50:53], v[174:177], v[182:185], v[50:53]
	v_mfma_f32_16x16x32_bf16 v[38:41], v[166:169], v[190:193], v[38:41]
	v_mfma_f32_16x16x32_bf16 v[34:37], v[174:177], v[190:193], v[34:37]
	v_mfma_f32_16x16x32_bf16 v[22:25], v[166:169], v[198:201], v[22:25]
	v_mfma_f32_16x16x32_bf16 v[18:21], v[174:177], v[198:201], v[18:21]
	v_mfma_f32_16x16x32_bf16 v[6:9], v[166:169], v[206:209], v[6:9]
	v_mfma_f32_16x16x32_bf16 v[2:5], v[174:177], v[206:209], v[2:5]
	s_setprio 0
	s_barrier
	s_add_i32 s63, 0, 0x18000
	s_add_i32 s70, 0, 0x1c000
	v_add_u32_e32 v158, s63, v143
	v_add_u32_e32 v174, s70, v143
	ds_read_b128 v[146:149], v158
	ds_read_b128 v[150:153], v158 offset:1024
	ds_read_b128 v[154:157], v158 offset:2048
	ds_read_b128 v[158:161], v158 offset:3072
	ds_read_b128 v[162:165], v174
	ds_read_b128 v[166:169], v174 offset:1024
	ds_read_b128 v[170:173], v174 offset:2048
	ds_read_b128 v[174:177], v174 offset:3072
	s_add_u32 s30, s30, 0x40000
	s_addc_u32 s31, s31, 0
	s_mov_b32 m0, s44
	v_lshl_add_u64 v[216:217], s[30:31], 0, v[130:131]
	ds_read_b128 v[178:181], v145 offset:32768
	ds_read_b128 v[182:185], v145 offset:33792
	ds_read_b128 v[186:189], v145 offset:34816
	ds_read_b128 v[190:193], v145 offset:35840
	ds_read_b128 v[194:197], v145 offset:36864
	ds_read_b128 v[198:201], v145 offset:37888
	ds_read_b128 v[202:205], v145 offset:38912
	ds_read_b128 v[206:209], v145 offset:39936
	global_load_lds_dwordx4 v[216:217], off
	v_lshl_add_u64 v[216:217], s[30:31], 0, v[132:133]
	s_mov_b32 m0, s45
	s_nop 0
	global_load_lds_dwordx4 v[216:217], off
	s_waitcnt vmcnt(8)
	s_waitcnt lgkmcnt(0)
	s_barrier
	s_setprio 1
	s_waitcnt lgkmcnt(0)
	v_mfma_f32_16x16x32_bf16 v[126:129], v[146:149], v[178:181], v[126:129]
	v_mfma_f32_16x16x32_bf16 v[122:125], v[154:157], v[178:181], v[122:125]
	v_mfma_f32_16x16x32_bf16 v[110:113], v[146:149], v[186:189], v[110:113]
	v_mfma_f32_16x16x32_bf16 v[106:109], v[154:157], v[186:189], v[106:109]
	v_mfma_f32_16x16x32_bf16 v[94:97], v[146:149], v[194:197], v[94:97]
	v_mfma_f32_16x16x32_bf16 v[90:93], v[154:157], v[194:197], v[90:93]
	v_mfma_f32_16x16x32_bf16 v[78:81], v[146:149], v[202:205], v[78:81]
	v_mfma_f32_16x16x32_bf16 v[74:77], v[154:157], v[202:205], v[74:77]
	v_mfma_f32_16x16x32_bf16 v[126:129], v[150:153], v[182:185], v[126:129]
	v_mfma_f32_16x16x32_bf16 v[122:125], v[158:161], v[182:185], v[122:125]
	v_mfma_f32_16x16x32_bf16 v[110:113], v[150:153], v[190:193], v[110:113]
	v_mfma_f32_16x16x32_bf16 v[106:109], v[158:161], v[190:193], v[106:109]
	v_mfma_f32_16x16x32_bf16 v[94:97], v[150:153], v[198:201], v[94:97]
	v_mfma_f32_16x16x32_bf16 v[90:93], v[158:161], v[198:201], v[90:93]
	v_mfma_f32_16x16x32_bf16 v[78:81], v[150:153], v[206:209], v[78:81]
	v_mfma_f32_16x16x32_bf16 v[74:77], v[158:161], v[206:209], v[74:77]
	s_setprio 0
	s_setprio 1
	v_mfma_f32_16x16x32_bf16 v[118:121], v[162:165], v[178:181], v[118:121]
	v_mfma_f32_16x16x32_bf16 v[114:117], v[170:173], v[178:181], v[114:117]
	v_mfma_f32_16x16x32_bf16 v[102:105], v[162:165], v[186:189], v[102:105]
	v_mfma_f32_16x16x32_bf16 v[98:101], v[170:173], v[186:189], v[98:101]
	v_mfma_f32_16x16x32_bf16 v[86:89], v[162:165], v[194:197], v[86:89]
	v_mfma_f32_16x16x32_bf16 v[82:85], v[170:173], v[194:197], v[82:85]
	v_mfma_f32_16x16x32_bf16 v[70:73], v[162:165], v[202:205], v[70:73]
	v_mfma_f32_16x16x32_bf16 v[66:69], v[170:173], v[202:205], v[66:69]
	v_mfma_f32_16x16x32_bf16 v[118:121], v[166:169], v[182:185], v[118:121]
	v_mfma_f32_16x16x32_bf16 v[114:117], v[174:177], v[182:185], v[114:117]
	v_mfma_f32_16x16x32_bf16 v[102:105], v[166:169], v[190:193], v[102:105]
	v_mfma_f32_16x16x32_bf16 v[98:101], v[174:177], v[190:193], v[98:101]
	v_mfma_f32_16x16x32_bf16 v[86:89], v[166:169], v[198:201], v[86:89]
	v_mfma_f32_16x16x32_bf16 v[82:85], v[174:177], v[198:201], v[82:85]
	v_mfma_f32_16x16x32_bf16 v[70:73], v[166:169], v[206:209], v[70:73]
	v_mfma_f32_16x16x32_bf16 v[66:69], v[174:177], v[206:209], v[66:69]
	s_setprio 0
	s_barrier
	s_add_i32 s30, s63, s40
	v_lshl_add_u64 v[140:141], v[140:141], 0, s[76:77]
	s_mov_b32 m0, s30
	ds_read_b128 v[178:181], v145 offset:49152
	ds_read_b128 v[182:185], v145 offset:50176
	ds_read_b128 v[186:189], v145 offset:51200
	ds_read_b128 v[190:193], v145 offset:52224
	ds_read_b128 v[194:197], v145 offset:53248
	ds_read_b128 v[198:201], v145 offset:54272
	ds_read_b128 v[202:205], v145 offset:55296
	ds_read_b128 v[206:209], v145 offset:56320
	global_load_lds_dwordx4 v[140:141], off
	s_add_i32 m0, s30, 0x2000
	s_add_u32 s28, s28, 0x40080
	v_lshl_add_u64 v[140:141], v[210:211], 0, s[76:77]
	s_addc_u32 s29, s29, 0
	s_add_i32 s30, s70, s40
	global_load_lds_dwordx4 v[140:141], off
	v_lshl_add_u64 v[140:141], s[28:29], 0, v[0:1]
	s_mov_b32 m0, s30
	s_nop 0
	global_load_lds_dwordx4 v[140:141], off
	v_lshl_add_u64 v[140:141], s[28:29], 0, v[134:135]
	s_add_i32 m0, s30, 0x2000
	s_nop 0
	global_load_lds_dwordx4 v[140:141], off
	v_lshl_add_u64 v[140:141], v[212:213], 0, s[76:77]
	s_mov_b32 m0, s46
	s_nop 0
	global_load_lds_dwordx4 v[140:141], off
	v_lshl_add_u64 v[140:141], v[214:215], 0, s[76:77]
	s_mov_b32 m0, s47
	s_nop 0
	global_load_lds_dwordx4 v[140:141], off
	s_waitcnt vmcnt(8)
	s_waitcnt lgkmcnt(0)
	s_barrier
	s_setprio 1
	s_waitcnt lgkmcnt(0)
	v_mfma_f32_16x16x32_bf16 v[62:65], v[146:149], v[178:181], v[62:65]
	v_mfma_f32_16x16x32_bf16 v[58:61], v[154:157], v[178:181], v[58:61]
	v_mfma_f32_16x16x32_bf16 v[46:49], v[146:149], v[186:189], v[46:49]
	v_mfma_f32_16x16x32_bf16 v[42:45], v[154:157], v[186:189], v[42:45]
	v_mfma_f32_16x16x32_bf16 v[30:33], v[146:149], v[194:197], v[30:33]
	v_mfma_f32_16x16x32_bf16 v[26:29], v[154:157], v[194:197], v[26:29]
	v_mfma_f32_16x16x32_bf16 v[14:17], v[146:149], v[202:205], v[14:17]
	v_mfma_f32_16x16x32_bf16 v[10:13], v[154:157], v[202:205], v[10:13]
	v_mfma_f32_16x16x32_bf16 v[62:65], v[150:153], v[182:185], v[62:65]
	v_mfma_f32_16x16x32_bf16 v[58:61], v[158:161], v[182:185], v[58:61]
	v_mfma_f32_16x16x32_bf16 v[46:49], v[150:153], v[190:193], v[46:49]
	v_mfma_f32_16x16x32_bf16 v[42:45], v[158:161], v[190:193], v[42:45]
	v_mfma_f32_16x16x32_bf16 v[30:33], v[150:153], v[198:201], v[30:33]
	v_mfma_f32_16x16x32_bf16 v[26:29], v[158:161], v[198:201], v[26:29]
	v_mfma_f32_16x16x32_bf16 v[14:17], v[150:153], v[206:209], v[14:17]
	v_mfma_f32_16x16x32_bf16 v[10:13], v[158:161], v[206:209], v[10:13]
	s_setprio 0
	s_setprio 1
	s_add_i32 s62, s62, 2
	s_add_u32 s53, s53, 0x100
	s_addc_u32 s61, s61, 0
	s_add_u32 s24, s24, 0x100
	s_addc_u32 s25, s25, 0
	s_add_u32 s28, s24, 0xfffc0080
	s_addc_u32 s29, s25, -1
	s_add_i32 s63, 0, 0x10000
	s_cmp_eq_u32 s62, 12
	s_cselect_b32 s31, s17, s29
	s_cselect_b32 s30, s51, s28
	v_add_u32_e32 v140, s63, v143
	s_cselect_b32 s29, s15, s61
	s_cselect_b32 s28, s52, s53
	s_add_i32 s72, 0, 0x14000
	s_cmp_gt_u32 s62, 13
	v_mfma_f32_16x16x32_bf16 v[54:57], v[162:165], v[178:181], v[54:57]
	v_mfma_f32_16x16x32_bf16 v[50:53], v[170:173], v[178:181], v[50:53]
	v_mfma_f32_16x16x32_bf16 v[38:41], v[162:165], v[186:189], v[38:41]
	v_mfma_f32_16x16x32_bf16 v[34:37], v[170:173], v[186:189], v[34:37]
	v_mfma_f32_16x16x32_bf16 v[22:25], v[162:165], v[194:197], v[22:25]
	v_mfma_f32_16x16x32_bf16 v[18:21], v[170:173], v[194:197], v[18:21]
	v_mfma_f32_16x16x32_bf16 v[6:9], v[162:165], v[202:205], v[6:9]
	v_mfma_f32_16x16x32_bf16 v[2:5], v[170:173], v[202:205], v[2:5]
	v_mfma_f32_16x16x32_bf16 v[54:57], v[166:169], v[182:185], v[54:57]
	v_mfma_f32_16x16x32_bf16 v[50:53], v[174:177], v[182:185], v[50:53]
	v_mfma_f32_16x16x32_bf16 v[38:41], v[166:169], v[190:193], v[38:41]
	v_mfma_f32_16x16x32_bf16 v[34:37], v[174:177], v[190:193], v[34:37]
	v_mfma_f32_16x16x32_bf16 v[22:25], v[166:169], v[198:201], v[22:25]
	v_mfma_f32_16x16x32_bf16 v[18:21], v[174:177], v[198:201], v[18:21]
	v_mfma_f32_16x16x32_bf16 v[6:9], v[166:169], v[206:209], v[6:9]
	v_mfma_f32_16x16x32_bf16 v[2:5], v[174:177], v[206:209], v[2:5]
	s_setprio 0
	s_barrier
.LBB0_1002:
	ds_read_b128 v[146:149], v140
	ds_read_b128 v[150:153], v140 offset:1024
	ds_read_b128 v[154:157], v140 offset:2048
	ds_read_b128 v[158:161], v140 offset:3072
	v_add_u32_e32 v140, s72, v143
	ds_read_b128 v[162:165], v140
	ds_read_b128 v[166:169], v140 offset:1024
	ds_read_b128 v[170:173], v140 offset:2048
	ds_read_b128 v[174:177], v140 offset:3072
	v_lshl_add_u64 v[140:141], s[24:25], 0, v[138:139]
	s_add_i32 m0, s23, 0xc000
	ds_read_b128 v[178:181], v145
	ds_read_b128 v[182:185], v145 offset:1024
	ds_read_b128 v[186:189], v145 offset:2048
	ds_read_b128 v[190:193], v145 offset:3072
	ds_read_b128 v[194:197], v145 offset:4096
	ds_read_b128 v[198:201], v145 offset:5120
	ds_read_b128 v[202:205], v145 offset:6144
	ds_read_b128 v[206:209], v145 offset:7168
	global_load_lds_dwordx4 v[140:141], off
	v_lshl_add_u64 v[140:141], s[24:25], 0, v[136:137]
	s_add_i32 m0, s23, 0xe000
	s_nop 0
	global_load_lds_dwordx4 v[140:141], off
	s_waitcnt vmcnt(8)
	s_waitcnt lgkmcnt(0)
	s_barrier
	s_setprio 1
	s_waitcnt lgkmcnt(0)
	v_mfma_f32_16x16x32_bf16 v[126:129], v[146:149], v[178:181], v[126:129]
	v_mfma_f32_16x16x32_bf16 v[122:125], v[154:157], v[178:181], v[122:125]
	v_mfma_f32_16x16x32_bf16 v[110:113], v[146:149], v[186:189], v[110:113]
	v_mfma_f32_16x16x32_bf16 v[106:109], v[154:157], v[186:189], v[106:109]
	v_mfma_f32_16x16x32_bf16 v[94:97], v[146:149], v[194:197], v[94:97]
	v_mfma_f32_16x16x32_bf16 v[90:93], v[154:157], v[194:197], v[90:93]
	v_mfma_f32_16x16x32_bf16 v[78:81], v[146:149], v[202:205], v[78:81]
	v_mfma_f32_16x16x32_bf16 v[74:77], v[154:157], v[202:205], v[74:77]
	v_mfma_f32_16x16x32_bf16 v[126:129], v[150:153], v[182:185], v[126:129]
	v_mfma_f32_16x16x32_bf16 v[122:125], v[158:161], v[182:185], v[122:125]
	v_mfma_f32_16x16x32_bf16 v[110:113], v[150:153], v[190:193], v[110:113]
	v_mfma_f32_16x16x32_bf16 v[106:109], v[158:161], v[190:193], v[106:109]
	v_mfma_f32_16x16x32_bf16 v[94:97], v[150:153], v[198:201], v[94:97]
	v_mfma_f32_16x16x32_bf16 v[90:93], v[158:161], v[198:201], v[90:93]
	v_mfma_f32_16x16x32_bf16 v[78:81], v[150:153], v[206:209], v[78:81]
	v_mfma_f32_16x16x32_bf16 v[74:77], v[158:161], v[206:209], v[74:77]
	s_setprio 0
	s_setprio 1
	v_mfma_f32_16x16x32_bf16 v[118:121], v[162:165], v[178:181], v[118:121]
	v_mfma_f32_16x16x32_bf16 v[114:117], v[170:173], v[178:181], v[114:117]
	v_mfma_f32_16x16x32_bf16 v[102:105], v[162:165], v[186:189], v[102:105]
	v_mfma_f32_16x16x32_bf16 v[98:101], v[170:173], v[186:189], v[98:101]
	v_mfma_f32_16x16x32_bf16 v[86:89], v[162:165], v[194:197], v[86:89]
	v_mfma_f32_16x16x32_bf16 v[82:85], v[170:173], v[194:197], v[82:85]
	v_mfma_f32_16x16x32_bf16 v[70:73], v[162:165], v[202:205], v[70:73]
	v_mfma_f32_16x16x32_bf16 v[66:69], v[170:173], v[202:205], v[66:69]
	v_mfma_f32_16x16x32_bf16 v[118:121], v[166:169], v[182:185], v[118:121]
	v_mfma_f32_16x16x32_bf16 v[114:117], v[174:177], v[182:185], v[114:117]
	v_mfma_f32_16x16x32_bf16 v[102:105], v[166:169], v[190:193], v[102:105]
	v_mfma_f32_16x16x32_bf16 v[98:101], v[174:177], v[190:193], v[98:101]
	v_mfma_f32_16x16x32_bf16 v[86:89], v[166:169], v[198:201], v[86:89]
	v_mfma_f32_16x16x32_bf16 v[82:85], v[174:177], v[198:201], v[82:85]
	v_mfma_f32_16x16x32_bf16 v[70:73], v[166:169], v[206:209], v[70:73]
	v_mfma_f32_16x16x32_bf16 v[66:69], v[174:177], v[206:209], v[66:69]
	s_setprio 0
	s_barrier
	s_add_i32 s63, s63, s40
	v_lshl_add_u64 v[140:141], s[28:29], 0, v[0:1]
	s_mov_b32 m0, s63
	ds_read_b128 v[178:181], v145 offset:16384
	ds_read_b128 v[182:185], v145 offset:17408
	ds_read_b128 v[186:189], v145 offset:18432
	ds_read_b128 v[190:193], v145 offset:19456
	ds_read_b128 v[194:197], v145 offset:20480
	ds_read_b128 v[198:201], v145 offset:21504
	ds_read_b128 v[202:205], v145 offset:22528
	ds_read_b128 v[206:209], v145 offset:23552
	global_load_lds_dwordx4 v[140:141], off
	s_add_i32 m0, s63, 0x2000
	s_add_u32 s70, s28, 0x40000
	v_lshl_add_u64 v[210:211], s[28:29], 0, v[134:135]
	s_addc_u32 s71, s29, 0
	s_add_i32 s63, s72, s40
	global_load_lds_dwordx4 v[210:211], off
	v_lshl_add_u64 v[212:213], s[70:71], 0, v[0:1]
	s_mov_b32 m0, s63
	v_lshl_add_u64 v[214:215], s[30:31], 0, v[132:133]
	global_load_lds_dwordx4 v[212:213], off
	v_lshl_add_u64 v[212:213], s[70:71], 0, v[134:135]
	s_add_i32 m0, s63, 0x2000
	s_nop 0
	global_load_lds_dwordx4 v[212:213], off
	v_lshl_add_u64 v[212:213], s[30:31], 0, v[130:131]
	s_mov_b32 m0, s23
	s_nop 0
	global_load_lds_dwordx4 v[212:213], off
	s_mov_b32 m0, s43
	s_nop 0
	global_load_lds_dwordx4 v[214:215], off
	s_waitcnt vmcnt(8)
	s_waitcnt lgkmcnt(0)
	s_barrier
	s_setprio 1
	s_waitcnt lgkmcnt(0)
	v_mfma_f32_16x16x32_bf16 v[62:65], v[146:149], v[178:181], v[62:65]
	v_mfma_f32_16x16x32_bf16 v[58:61], v[154:157], v[178:181], v[58:61]
	v_mfma_f32_16x16x32_bf16 v[46:49], v[146:149], v[186:189], v[46:49]
	v_mfma_f32_16x16x32_bf16 v[42:45], v[154:157], v[186:189], v[42:45]
	v_mfma_f32_16x16x32_bf16 v[30:33], v[146:149], v[194:197], v[30:33]
	v_mfma_f32_16x16x32_bf16 v[26:29], v[154:157], v[194:197], v[26:29]
	v_mfma_f32_16x16x32_bf16 v[14:17], v[146:149], v[202:205], v[14:17]
	v_mfma_f32_16x16x32_bf16 v[10:13], v[154:157], v[202:205], v[10:13]
	v_mfma_f32_16x16x32_bf16 v[62:65], v[150:153], v[182:185], v[62:65]
	v_mfma_f32_16x16x32_bf16 v[58:61], v[158:161], v[182:185], v[58:61]
	v_mfma_f32_16x16x32_bf16 v[46:49], v[150:153], v[190:193], v[46:49]
	v_mfma_f32_16x16x32_bf16 v[42:45], v[158:161], v[190:193], v[42:45]
	v_mfma_f32_16x16x32_bf16 v[30:33], v[150:153], v[198:201], v[30:33]
	v_mfma_f32_16x16x32_bf16 v[26:29], v[158:161], v[198:201], v[26:29]
	v_mfma_f32_16x16x32_bf16 v[14:17], v[150:153], v[206:209], v[14:17]
	v_mfma_f32_16x16x32_bf16 v[10:13], v[158:161], v[206:209], v[10:13]
	s_setprio 0
	s_setprio 1
	v_mfma_f32_16x16x32_bf16 v[54:57], v[162:165], v[178:181], v[54:57]
	v_mfma_f32_16x16x32_bf16 v[50:53], v[170:173], v[178:181], v[50:53]
	v_mfma_f32_16x16x32_bf16 v[38:41], v[162:165], v[186:189], v[38:41]
	v_mfma_f32_16x16x32_bf16 v[34:37], v[170:173], v[186:189], v[34:37]
	v_mfma_f32_16x16x32_bf16 v[22:25], v[162:165], v[194:197], v[22:25]
	v_mfma_f32_16x16x32_bf16 v[18:21], v[170:173], v[194:197], v[18:21]
	v_mfma_f32_16x16x32_bf16 v[6:9], v[162:165], v[202:205], v[6:9]
	v_mfma_f32_16x16x32_bf16 v[2:5], v[170:173], v[202:205], v[2:5]
	v_mfma_f32_16x16x32_bf16 v[54:57], v[166:169], v[182:185], v[54:57]
	v_mfma_f32_16x16x32_bf16 v[50:53], v[174:177], v[182:185], v[50:53]
	v_mfma_f32_16x16x32_bf16 v[38:41], v[166:169], v[190:193], v[38:41]
	v_mfma_f32_16x16x32_bf16 v[34:37], v[174:177], v[190:193], v[34:37]
	v_mfma_f32_16x16x32_bf16 v[22:25], v[166:169], v[198:201], v[22:25]
	v_mfma_f32_16x16x32_bf16 v[18:21], v[174:177], v[198:201], v[18:21]
	v_mfma_f32_16x16x32_bf16 v[6:9], v[166:169], v[206:209], v[6:9]
	v_mfma_f32_16x16x32_bf16 v[2:5], v[174:177], v[206:209], v[2:5]
	s_setprio 0
	s_barrier
	s_add_i32 s63, 0, 0x18000
	s_add_i32 s70, 0, 0x1c000
	v_add_u32_e32 v158, s63, v143
	v_add_u32_e32 v174, s70, v143
	ds_read_b128 v[146:149], v158
	ds_read_b128 v[150:153], v158 offset:1024
	ds_read_b128 v[154:157], v158 offset:2048
	ds_read_b128 v[158:161], v158 offset:3072
	ds_read_b128 v[162:165], v174
	ds_read_b128 v[166:169], v174 offset:1024
	ds_read_b128 v[170:173], v174 offset:2048
	ds_read_b128 v[174:177], v174 offset:3072
	s_add_u32 s30, s30, 0x40000
	s_addc_u32 s31, s31, 0
	s_mov_b32 m0, s44
	v_lshl_add_u64 v[216:217], s[30:31], 0, v[130:131]
	ds_read_b128 v[178:181], v145 offset:32768
	ds_read_b128 v[182:185], v145 offset:33792
	ds_read_b128 v[186:189], v145 offset:34816
	ds_read_b128 v[190:193], v145 offset:35840
	ds_read_b128 v[194:197], v145 offset:36864
	ds_read_b128 v[198:201], v145 offset:37888
	ds_read_b128 v[202:205], v145 offset:38912
	ds_read_b128 v[206:209], v145 offset:39936
	global_load_lds_dwordx4 v[216:217], off
	v_lshl_add_u64 v[216:217], s[30:31], 0, v[132:133]
	s_mov_b32 m0, s45
	s_nop 0
	global_load_lds_dwordx4 v[216:217], off
	s_waitcnt vmcnt(8)
	s_waitcnt lgkmcnt(0)
	s_barrier
	s_setprio 1
	s_waitcnt lgkmcnt(0)
	v_mfma_f32_16x16x32_bf16 v[126:129], v[146:149], v[178:181], v[126:129]
	v_mfma_f32_16x16x32_bf16 v[122:125], v[154:157], v[178:181], v[122:125]
	v_mfma_f32_16x16x32_bf16 v[110:113], v[146:149], v[186:189], v[110:113]
	v_mfma_f32_16x16x32_bf16 v[106:109], v[154:157], v[186:189], v[106:109]
	v_mfma_f32_16x16x32_bf16 v[94:97], v[146:149], v[194:197], v[94:97]
	v_mfma_f32_16x16x32_bf16 v[90:93], v[154:157], v[194:197], v[90:93]
	v_mfma_f32_16x16x32_bf16 v[78:81], v[146:149], v[202:205], v[78:81]
	v_mfma_f32_16x16x32_bf16 v[74:77], v[154:157], v[202:205], v[74:77]
	v_mfma_f32_16x16x32_bf16 v[126:129], v[150:153], v[182:185], v[126:129]
	v_mfma_f32_16x16x32_bf16 v[122:125], v[158:161], v[182:185], v[122:125]
	v_mfma_f32_16x16x32_bf16 v[110:113], v[150:153], v[190:193], v[110:113]
	v_mfma_f32_16x16x32_bf16 v[106:109], v[158:161], v[190:193], v[106:109]
	v_mfma_f32_16x16x32_bf16 v[94:97], v[150:153], v[198:201], v[94:97]
	v_mfma_f32_16x16x32_bf16 v[90:93], v[158:161], v[198:201], v[90:93]
	v_mfma_f32_16x16x32_bf16 v[78:81], v[150:153], v[206:209], v[78:81]
	v_mfma_f32_16x16x32_bf16 v[74:77], v[158:161], v[206:209], v[74:77]
	s_setprio 0
	s_setprio 1
	v_mfma_f32_16x16x32_bf16 v[118:121], v[162:165], v[178:181], v[118:121]
	v_mfma_f32_16x16x32_bf16 v[114:117], v[170:173], v[178:181], v[114:117]
	v_mfma_f32_16x16x32_bf16 v[102:105], v[162:165], v[186:189], v[102:105]
	v_mfma_f32_16x16x32_bf16 v[98:101], v[170:173], v[186:189], v[98:101]
	v_mfma_f32_16x16x32_bf16 v[86:89], v[162:165], v[194:197], v[86:89]
	v_mfma_f32_16x16x32_bf16 v[82:85], v[170:173], v[194:197], v[82:85]
	v_mfma_f32_16x16x32_bf16 v[70:73], v[162:165], v[202:205], v[70:73]
	v_mfma_f32_16x16x32_bf16 v[66:69], v[170:173], v[202:205], v[66:69]
	v_mfma_f32_16x16x32_bf16 v[118:121], v[166:169], v[182:185], v[118:121]
	v_mfma_f32_16x16x32_bf16 v[114:117], v[174:177], v[182:185], v[114:117]
	v_mfma_f32_16x16x32_bf16 v[102:105], v[166:169], v[190:193], v[102:105]
	v_mfma_f32_16x16x32_bf16 v[98:101], v[174:177], v[190:193], v[98:101]
	v_mfma_f32_16x16x32_bf16 v[86:89], v[166:169], v[198:201], v[86:89]
	v_mfma_f32_16x16x32_bf16 v[82:85], v[174:177], v[198:201], v[82:85]
	v_mfma_f32_16x16x32_bf16 v[70:73], v[166:169], v[206:209], v[70:73]
	v_mfma_f32_16x16x32_bf16 v[66:69], v[174:177], v[206:209], v[66:69]
	s_setprio 0
	s_barrier
	s_add_i32 s30, s63, s40
	v_lshl_add_u64 v[140:141], v[140:141], 0, s[76:77]
	s_mov_b32 m0, s30
	ds_read_b128 v[178:181], v145 offset:49152
	ds_read_b128 v[182:185], v145 offset:50176
	ds_read_b128 v[186:189], v145 offset:51200
	ds_read_b128 v[190:193], v145 offset:52224
	ds_read_b128 v[194:197], v145 offset:53248
	ds_read_b128 v[198:201], v145 offset:54272
	ds_read_b128 v[202:205], v145 offset:55296
	ds_read_b128 v[206:209], v145 offset:56320
	global_load_lds_dwordx4 v[140:141], off
	s_add_i32 m0, s30, 0x2000
	s_add_u32 s28, s28, 0x40080
	v_lshl_add_u64 v[140:141], v[210:211], 0, s[76:77]
	s_addc_u32 s29, s29, 0
	s_add_i32 s30, s70, s40
	global_load_lds_dwordx4 v[140:141], off
	v_lshl_add_u64 v[140:141], s[28:29], 0, v[0:1]
	s_mov_b32 m0, s30
	s_nop 0
	global_load_lds_dwordx4 v[140:141], off
	v_lshl_add_u64 v[140:141], s[28:29], 0, v[134:135]
	s_add_i32 m0, s30, 0x2000
	s_nop 0
	global_load_lds_dwordx4 v[140:141], off
	v_lshl_add_u64 v[140:141], v[212:213], 0, s[76:77]
	s_mov_b32 m0, s46
	s_nop 0
	global_load_lds_dwordx4 v[140:141], off
	v_lshl_add_u64 v[140:141], v[214:215], 0, s[76:77]
	s_mov_b32 m0, s47
	s_nop 0
	global_load_lds_dwordx4 v[140:141], off
	s_waitcnt vmcnt(8)
	s_waitcnt lgkmcnt(0)
	s_barrier
	s_setprio 1
	s_waitcnt lgkmcnt(0)
	v_mfma_f32_16x16x32_bf16 v[62:65], v[146:149], v[178:181], v[62:65]
	v_mfma_f32_16x16x32_bf16 v[58:61], v[154:157], v[178:181], v[58:61]
	v_mfma_f32_16x16x32_bf16 v[46:49], v[146:149], v[186:189], v[46:49]
	v_mfma_f32_16x16x32_bf16 v[42:45], v[154:157], v[186:189], v[42:45]
	v_mfma_f32_16x16x32_bf16 v[30:33], v[146:149], v[194:197], v[30:33]
	v_mfma_f32_16x16x32_bf16 v[26:29], v[154:157], v[194:197], v[26:29]
	v_mfma_f32_16x16x32_bf16 v[14:17], v[146:149], v[202:205], v[14:17]
	v_mfma_f32_16x16x32_bf16 v[10:13], v[154:157], v[202:205], v[10:13]
	v_mfma_f32_16x16x32_bf16 v[62:65], v[150:153], v[182:185], v[62:65]
	v_mfma_f32_16x16x32_bf16 v[58:61], v[158:161], v[182:185], v[58:61]
	v_mfma_f32_16x16x32_bf16 v[46:49], v[150:153], v[190:193], v[46:49]
	v_mfma_f32_16x16x32_bf16 v[42:45], v[158:161], v[190:193], v[42:45]
	v_mfma_f32_16x16x32_bf16 v[30:33], v[150:153], v[198:201], v[30:33]
	v_mfma_f32_16x16x32_bf16 v[26:29], v[158:161], v[198:201], v[26:29]
	v_mfma_f32_16x16x32_bf16 v[14:17], v[150:153], v[206:209], v[14:17]
	v_mfma_f32_16x16x32_bf16 v[10:13], v[158:161], v[206:209], v[10:13]
	s_setprio 0
	s_setprio 1
	s_add_i32 s62, s62, 2
	s_add_u32 s53, s53, 0x100
	s_addc_u32 s61, s61, 0
	s_add_u32 s24, s24, 0x100
	s_addc_u32 s25, s25, 0
	s_add_u32 s28, s24, 0xfffc0080
	s_addc_u32 s29, s25, -1
	s_add_i32 s63, 0, 0x10000
	s_cmp_eq_u32 s62, 12
	s_cselect_b32 s31, s17, s29
	s_cselect_b32 s30, s51, s28
	v_add_u32_e32 v140, s63, v143
	s_cselect_b32 s29, s15, s61
	s_cselect_b32 s28, s52, s53
	s_add_i32 s72, 0, 0x14000
	s_cmp_gt_u32 s62, 13
	v_mfma_f32_16x16x32_bf16 v[54:57], v[162:165], v[178:181], v[54:57]
	v_mfma_f32_16x16x32_bf16 v[50:53], v[170:173], v[178:181], v[50:53]
	v_mfma_f32_16x16x32_bf16 v[38:41], v[162:165], v[186:189], v[38:41]
	v_mfma_f32_16x16x32_bf16 v[34:37], v[170:173], v[186:189], v[34:37]
	v_mfma_f32_16x16x32_bf16 v[22:25], v[162:165], v[194:197], v[22:25]
	v_mfma_f32_16x16x32_bf16 v[18:21], v[170:173], v[194:197], v[18:21]
	v_mfma_f32_16x16x32_bf16 v[6:9], v[162:165], v[202:205], v[6:9]
	v_mfma_f32_16x16x32_bf16 v[2:5], v[170:173], v[202:205], v[2:5]
	v_mfma_f32_16x16x32_bf16 v[54:57], v[166:169], v[182:185], v[54:57]
	v_mfma_f32_16x16x32_bf16 v[50:53], v[174:177], v[182:185], v[50:53]
	v_mfma_f32_16x16x32_bf16 v[38:41], v[166:169], v[190:193], v[38:41]
	v_mfma_f32_16x16x32_bf16 v[34:37], v[174:177], v[190:193], v[34:37]
	v_mfma_f32_16x16x32_bf16 v[22:25], v[166:169], v[198:201], v[22:25]
	v_mfma_f32_16x16x32_bf16 v[18:21], v[174:177], v[198:201], v[18:21]
	v_mfma_f32_16x16x32_bf16 v[6:9], v[166:169], v[206:209], v[6:9]
	v_mfma_f32_16x16x32_bf16 v[2:5], v[174:177], v[206:209], v[2:5]
	s_setprio 0
	s_barrier
	s_cbranch_scc0 .LBB0_1002
	s_and_b64 vcc, exec, s[10:11]
	s_cbranch_vccz .LBB0_1005
	s_barrier
